# v33 + SGU LDS bank-conflict fix: 16B-chunk XOR swizzle of the transposed v tile (staging ds_write_b16 16-way conflict -> 2-way), reader immediates/lane base adjusted
# speedup vs baseline: 1.0089x; 1.0089x over previous
; __device__ __forceinline__ void sgu_phase(const Params& p, int o, char* lds) {
;     ...
;   const int tid = tid_, wave = tid >> 6, lane = tid & 63, fr = lane & 15, quad = lane >> 4;
;   const int wr = wave >> 1, wc = wave & 1;
;   const bf16* big = (const bf16*)(p.ws + WS_BIG); bf16* mix = (bf16*)(p.ws + WS_MIX);
;   const bf16* Wb = (const bf16*)(p.ws + WS_W) + W_SGW + (size_t)o * 8 * 128 * 128;
;   const unsigned long long* vss = (const unsigned long long*)(p.ws + WS_SS) + (size_t)(9 + o) * T;
;   float* rs = (float*)(lds + OFF_RS);
;   const int NU = 512 * 8, G = gridDim.x;
;   const bool gfix = (G & 7) == 0;
;   u32x4 wraw[4][2]; f32x4 gainv[4]; float biasv[2]; int gcur = -1;
;   const int sq0 = tid >> 4, sc8 = (tid & 15) * 8;
;   u32x4 vst[4]; unsigned long long vsn = 0;
;   int u = blockIdx.x;
;     ...
;     for (int i = 0; i < 4; ++i) { const int q = sq0 + 32 * i; const u32x4 w = vst[i];
;       unsigned short* d = (unsigned short*)(lds + OFF_VT + (sc8) * VT_PITCH + q * 2);
.LBB0_29:
	s_or_b64 exec, exec, s[26:27]
	v_readlane_b32 s26, v255, 20
	v_readlane_b32 s27, v255, 21
	s_lshl_b64 s[20:21], s[26:27], 18
	v_bfe_u32 v28, v16, 4, 2
	s_add_u32 s20, s18, s20
	s_addc_u32 s21, s19, s21
	v_lshlrev_b32_e32 v22, 4, v28
	v_mov_b32_e32 v23, v144
	v_ashrrev_i32_e32 v20, 2, v16
	v_lshl_add_u64 v[24:25], s[20:21], 0, v[22:23]
	s_mov_b64 s[20:21], 0x6a00000
	v_lshl_add_u64 v[76:77], v[16:17], 3, s[0:1]
	s_mov_b64 s[0:1], 0x6a00040
	v_and_b32_e32 v19, 15, v16
	v_and_b32_e32 v26, 0xffffffe0, v20
	v_lshl_add_u64 v[72:73], v[24:25], 0, s[20:21]
	s_lshl_b32 s20, s26, 10
	v_lshl_add_u64 v[78:79], v[24:25], 0, s[0:1]
	s_mov_b64 s[0:1], 0x6a00080
	v_and_b32_e32 v29, 64, v16
	v_or_b32_e32 v70, v26, v19
	s_ashr_i32 s21, s20, 31
	v_or_b32_e32 v19, s20, v19
	v_lshl_add_u64 v[80:81], v[24:25], 0, s[0:1]
	s_mov_b64 s[0:1], 0x6a000c0
	v_ashrrev_i32_e32 v71, 31, v26
	v_add_u32_e32 v91, v19, v26
	v_lshlrev_b32_e32 v26, 1, v29
	v_mov_b32_e32 v27, v144
	v_lshl_add_u64 v[82:83], v[24:25], 0, s[0:1]
	s_lshl_b64 s[0:1], s[20:21], 2
	v_readlane_b32 s52, v254, 54
	v_lshlrev_b32_e32 v20, 3, v28
	v_mov_b32_e32 v21, v144
	v_lshl_add_u64 v[26:27], s[30:31], 0, v[26:27]
	v_lshl_add_u32 v93, v16, 2, 0
	v_and_b32_e32 v16, 0x4f, v16
	v_readlane_b32 s53, v254, 55
	s_add_u32 s0, s52, s0
	v_lshl_add_u64 v[74:75], v[26:27], 0, v[20:21]
	s_movk_i32 s2, 0x110
	v_lshl_add_u32 v110, v28, 5, 0
	v_mul_u32_u24_e32 v21, 0x110, v16
	s_addc_u32 s1, s53, s1
	v_lshlrev_b32_e32 v16, 2, v29
	v_mov_b32_e32 v17, v144
	v_mad_u32_u24 v18, v18, s2, 0
	v_lshlrev_b32_e32 v19, 1, v64
	v_sub_u32_e32 v20, v110, v22
	v_or_b32_e32 v86, 16, v70
	v_lshl_add_u64 v[16:17], s[0:1], 0, v[16:17]
	v_lshl_or_b32 v111, v28, 2, v29
	v_ashrrev_i32_e32 v85, 31, v70
	v_mov_b32_e32 v84, v70
	v_ashrrev_i32_e32 v87, 31, v86
	v_lshl_add_u64 v[88:89], v[16:17], 0, v[22:23]
	s_mov_b32 s10, -1
	v_add_u32_e32 v112, v18, v19
	v_add_u32_e32 v113, v20, v21
	v_and_b32_e32 v170, 8, v232
	v_lshlrev_b32_e32 v170, 2, v170
	v_and_b32_e32 v171, 1, v232
	v_lshl_or_b32 v170, v171, 4, v170
	v_xor_b32_e32 v170, v112, v170
	v_bfe_u32 v171, v232, 1, 2
	v_lshl_add_u32 v172, v171, 6, v170
	v_xor_b32_e32 v176, 1, v171
	v_lshl_add_u32 v173, v176, 6, v170
	v_xor_b32_e32 v176, 2, v171
	v_lshl_add_u32 v174, v176, 6, v170
	v_xor_b32_e32 v176, 3, v171
	v_lshl_add_u32 v175, v176, 6, v170
	v_lshrrev_b32_e32 v176, 1, v232
	v_and_b32_e32 v176, 32, v176
	v_and_b32_e32 v177, 8, v232
	v_lshl_or_b32 v176, v177, 1, v176
	v_xor_b32_e32 v176, v20, v176
	v_add_u32_e32 v113, v176, v21
	v_readlane_b32 s35, v254, 24
	s_mov_b32 s8, s76
	v_readlane_b32 s54, v254, 56
	v_readlane_b32 s55, v254, 57
	v_readlane_b32 s56, v254, 58
	v_readlane_b32 s57, v254, 59
	v_readlane_b32 s58, v254, 60
	v_readlane_b32 s59, v254, 61
	s_branch .LBB0_32

; __device__ __forceinline__ unsigned cvtpk(float lo, float hi) { unsigned r; asm volatile("v_cvt_pk_bf16_f32 %0, %1, %2" : "=v"(r) : "v"(lo), "v"(hi)); return r; }
; __device__ __forceinline__ float bflo(unsigned w) { return __uint_as_float(w << 16); }
; __device__ __forceinline__ float bfhi(unsigned w) { return __uint_as_float(w & 0xffff0000u); }
; __device__ __forceinline__ void sgu_phase(const Params& p, int o, char* lds) {
;     ...
; #pragma unroll
;     for (int kq = 0; kq < 4; ++kq) {
;       const f32x4 r0 = *(const f32x4*)(rs + kq * 32 + quad * 8), r1 = *(const f32x4*)(rs + kq * 32 + quad * 8 + 4);
;       bf16x8 wf[2];
; #pragma unroll
;       for (int nt = 0; nt < 2; ++nt) { const u32x4 w = wraw[kq][nt];
;         u32x4 s; s.x = cvtpk(bflo(w.x) * r0[0], bfhi(w.x) * r0[1]); s.y = cvtpk(bflo(w.y) * r0[2], bfhi(w.y) * r0[3]); s.z = cvtpk(bflo(w.z) * r1[0], bfhi(w.z) * r1[1]); s.w = cvtpk(bflo(w.w) * r1[2], bfhi(w.w) * r1[3]);
;         wf[nt] = __builtin_bit_cast(bf16x8, s); }
; #pragma unroll
;       for (int mt = 0; mt < 4; ++mt) { const bf16x8 vf = *(const bf16x8*)(lds + OFF_VT + (wc * 64 + mt * 16 + fr) * VT_PITCH + (kq * 32 + quad * 8) * 2);
; #pragma unroll
;         for (int nt = 0; nt < 2; ++nt) acc[mt][nt] = __builtin_amdgcn_mfma_f32_16x16x32_bf16(vf, wf[nt], acc[mt][nt], 0, 0, 0); }
.LBB0_31:
	ds_read_b128 v[114:117], v110 offset:34816
	ds_read_b128 v[118:121], v110 offset:34832
	v_lshlrev_b32_e32 v67, 16, v16
	v_and_b32_e32 v122, 0xffff0000, v16
	v_and_b32_e32 v123, 0xffff0000, v17
	s_waitcnt lgkmcnt(1)
	v_mul_f32_e32 v67, v114, v67
	v_mul_f32_e32 v122, v115, v122
	v_cvt_pk_bf16_f32 v122, v67, v122
	v_lshlrev_b32_e32 v67, 16, v17
	v_mul_f32_e32 v67, v116, v67
	v_mul_f32_e32 v123, v117, v123
	v_cvt_pk_bf16_f32 v123, v67, v123
	v_lshlrev_b32_e32 v67, 16, v18
	v_and_b32_e32 v124, 0xffff0000, v18
	s_waitcnt lgkmcnt(0)
	v_mul_f32_e32 v67, v118, v67
	v_mul_f32_e32 v124, v119, v124
	v_cvt_pk_bf16_f32 v124, v67, v124
	v_lshlrev_b32_e32 v67, 16, v19
	v_and_b32_e32 v125, 0xffff0000, v19
	v_mul_f32_e32 v67, v120, v67
	v_mul_f32_e32 v125, v121, v125
	v_cvt_pk_bf16_f32 v125, v67, v125
	v_lshlrev_b32_e32 v67, 16, v24
	v_mul_f32_e32 v67, v114, v67
	v_and_b32_e32 v114, 0xffff0000, v24
	v_mul_f32_e32 v114, v115, v114
	v_cvt_pk_bf16_f32 v114, v67, v114
	v_lshlrev_b32_e32 v67, 16, v25
	v_and_b32_e32 v115, 0xffff0000, v25
	v_mul_f32_e32 v67, v116, v67
	v_mul_f32_e32 v115, v117, v115
	v_cvt_pk_bf16_f32 v115, v67, v115
	v_lshlrev_b32_e32 v67, 16, v26
	v_and_b32_e32 v116, 0xffff0000, v26
	v_mul_f32_e32 v67, v118, v67
	v_mul_f32_e32 v116, v119, v116
	v_and_b32_e32 v117, 0xffff0000, v27
	v_cvt_pk_bf16_f32 v116, v67, v116
	v_lshlrev_b32_e32 v67, 16, v27
	v_mul_f32_e32 v117, v121, v117
	v_mul_f32_e32 v67, v120, v67
	v_cvt_pk_bf16_f32 v117, v67, v117
	ds_read_b128 v[118:121], v113
	ds_read_b128 v[130:133], v113 offset:4416
	ds_read_b128 v[138:141], v113 offset:8832
	ds_read_b128 v[156:159], v113 offset:13248
	s_waitcnt lgkmcnt(3)
	v_mfma_f32_16x16x32_bf16 v[126:129], v[118:121], v[122:125], 0
	v_lshlrev_b32_e32 v67, 16, v20
	v_and_b32_e32 v142, 0xffff0000, v20
	v_readlane_b32 s20, v255, 23
	v_mfma_f32_16x16x32_bf16 v[118:121], v[118:121], v[114:117], 0
	s_waitcnt vmcnt(7)
	v_lshlrev_b32_e32 v146, 16, v108
	v_and_b32_e32 v147, 0xffff0000, v108
	v_lshlrev_b32_e32 v108, 16, v109
	s_waitcnt lgkmcnt(2)
	v_mfma_f32_16x16x32_bf16 v[134:137], v[130:133], v[122:125], 0
	v_and_b32_e32 v109, 0xffff0000, v109
	v_readlane_b32 s21, v255, 24
	s_andn2_b64 vcc, exec, s[0:1]
	v_mfma_f32_16x16x32_bf16 v[130:133], v[130:133], v[114:117], 0
	s_waitcnt lgkmcnt(1)
	v_mfma_f32_16x16x32_bf16 v[152:155], v[138:141], v[122:125], 0
	v_mfma_f32_16x16x32_bf16 v[138:141], v[138:141], v[114:117], 0
	s_waitcnt lgkmcnt(0)
	v_mfma_f32_16x16x32_bf16 v[122:125], v[156:159], v[122:125], 0
	v_mfma_f32_16x16x32_bf16 v[114:117], v[156:159], v[114:117], 0
	ds_read_b128 v[156:159], v110 offset:34944
	ds_read_b128 v[160:163], v110 offset:34960
	s_waitcnt lgkmcnt(1)
	v_mul_f32_e32 v67, v156, v67
	v_mul_f32_e32 v142, v157, v142
	v_cvt_pk_bf16_f32 v164, v67, v142
	v_lshlrev_b32_e32 v67, 16, v21
	v_and_b32_e32 v142, 0xffff0000, v21
	v_mul_f32_e32 v67, v158, v67
	v_mul_f32_e32 v142, v159, v142
	v_cvt_pk_bf16_f32 v165, v67, v142
	v_lshlrev_b32_e32 v67, 16, v22
	v_and_b32_e32 v142, 0xffff0000, v22
	s_waitcnt lgkmcnt(0)
	v_mul_f32_e32 v67, v160, v67
	v_mul_f32_e32 v142, v161, v142
	v_cvt_pk_bf16_f32 v166, v67, v142
	v_lshlrev_b32_e32 v67, 16, v23
	v_and_b32_e32 v142, 0xffff0000, v23
	v_mul_f32_e32 v67, v162, v67
	v_mul_f32_e32 v142, v163, v142
	v_cvt_pk_bf16_f32 v167, v67, v142
	v_lshlrev_b32_e32 v67, 16, v28
	v_and_b32_e32 v142, 0xffff0000, v28
	v_mul_f32_e32 v67, v156, v67
	v_mul_f32_e32 v142, v157, v142
	v_cvt_pk_bf16_f32 v156, v67, v142
	v_lshlrev_b32_e32 v67, 16, v29
	v_and_b32_e32 v142, 0xffff0000, v29
	v_mul_f32_e32 v67, v158, v67
	v_mul_f32_e32 v142, v159, v142
	v_cvt_pk_bf16_f32 v157, v67, v142
	v_lshlrev_b32_e32 v67, 16, v30
	v_and_b32_e32 v142, 0xffff0000, v30
	v_mul_f32_e32 v67, v160, v67
	v_mul_f32_e32 v142, v161, v142
	v_cvt_pk_bf16_f32 v158, v67, v142
	v_lshlrev_b32_e32 v67, 16, v31
	v_and_b32_e32 v142, 0xffff0000, v31
	v_mul_f32_e32 v67, v162, v67
	v_mul_f32_e32 v142, v163, v142
	v_cvt_pk_bf16_f32 v159, v67, v142
	ds_read_b128 v[160:163], v113 offset:64
	s_waitcnt lgkmcnt(0)
	v_mfma_f32_16x16x32_bf16 v[126:129], v[160:163], v[164:167], v[126:129]
	v_lshlrev_b32_e32 v67, 16, v48
	v_and_b32_e32 v142, 0xffff0000, v48
	v_mfma_f32_16x16x32_bf16 v[118:121], v[160:163], v[156:159], v[118:121]
	ds_read_b128 v[160:163], v113 offset:4352
	s_waitcnt lgkmcnt(0)
	v_mfma_f32_16x16x32_bf16 v[134:137], v[160:163], v[164:167], v[134:137]
	v_mfma_f32_16x16x32_bf16 v[130:133], v[160:163], v[156:159], v[130:133]
	ds_read_b128 v[160:163], v113 offset:8896
	s_waitcnt lgkmcnt(0)
	v_mfma_f32_16x16x32_bf16 v[152:155], v[160:163], v[164:167], v[152:155]
	v_mfma_f32_16x16x32_bf16 v[138:141], v[160:163], v[156:159], v[138:141]
	ds_read_b128 v[160:163], v113 offset:13184
	s_waitcnt lgkmcnt(0)
	v_mfma_f32_16x16x32_bf16 v[122:125], v[160:163], v[164:167], v[122:125]
	v_mfma_f32_16x16x32_bf16 v[114:117], v[160:163], v[156:159], v[114:117]
	ds_read_b128 v[156:159], v110 offset:35072
	ds_read_b128 v[160:163], v110 offset:35088
	s_waitcnt lgkmcnt(1)
	v_mul_f32_e32 v67, v156, v67
	v_mul_f32_e32 v142, v157, v142
	v_cvt_pk_bf16_f32 v164, v67, v142
	v_lshlrev_b32_e32 v67, 16, v49
	v_and_b32_e32 v142, 0xffff0000, v49
	v_mul_f32_e32 v67, v158, v67
	v_mul_f32_e32 v142, v159, v142
	v_cvt_pk_bf16_f32 v165, v67, v142
	v_lshlrev_b32_e32 v67, 16, v50
	v_and_b32_e32 v142, 0xffff0000, v50
	s_waitcnt lgkmcnt(0)
; #define GAS __attribute__((address_space(1)))
; __device__ __forceinline__ unsigned cvtpk(float lo, float hi) { unsigned r; asm volatile("v_cvt_pk_bf16_f32 %0, %1, %2" : "=v"(r) : "v"(lo), "v"(hi)); return r; }
; __device__ __forceinline__ float bflo(unsigned w) { return __uint_as_float(w << 16); }
; __device__ __forceinline__ float bfhi(unsigned w) { return __uint_as_float(w & 0xffff0000u); }
; __device__ __forceinline__ void sgu_phase(const Params& p, int o, char* lds) {
;     ...
; #pragma unroll
;     for (int kq = 0; kq < 4; ++kq) {
;       const f32x4 r0 = *(const f32x4*)(rs + kq * 32 + quad * 8), r1 = *(const f32x4*)(rs + kq * 32 + quad * 8 + 4);
;       bf16x8 wf[2];
; #pragma unroll
;       for (int nt = 0; nt < 2; ++nt) { const u32x4 w = wraw[kq][nt];
;         u32x4 s; s.x = cvtpk(bflo(w.x) * r0[0], bfhi(w.x) * r0[1]); s.y = cvtpk(bflo(w.y) * r0[2], bfhi(w.y) * r0[3]); s.z = cvtpk(bflo(w.z) * r1[0], bfhi(w.z) * r1[1]); s.w = cvtpk(bflo(w.w) * r1[2], bfhi(w.w) * r1[3]);
;         wf[nt] = __builtin_bit_cast(bf16x8, s); }
; #pragma unroll
;       for (int mt = 0; mt < 4; ++mt) { const bf16x8 vf = *(const bf16x8*)(lds + OFF_VT + (wc * 64 + mt * 16 + fr) * VT_PITCH + (kq * 32 + quad * 8) * 2);
; #pragma unroll
;         for (int nt = 0; nt < 2; ++nt) acc[mt][nt] = __builtin_amdgcn_mfma_f32_16x16x32_bf16(vf, wf[nt], acc[mt][nt], 0, 0, 0); }
;     }
; #pragma unroll
;     for (int nt = 0; nt < 2; ++nt) { const int pp = wr * 32 + nt * 16 + fr;
; #pragma unroll
;       for (int mt = 0; mt < 4; ++mt) { const int c = g * 128 + wc * 64 + mt * 16 + 4 * quad; const u32x2 uu = uw[nt][mt];
;         const f32x4 v = (f32x4){bflo(uu.x), bfhi(uu.x), bflo(uu.y), bfhi(uu.y)} * (gainv[mt] * acc[mt][nt] + biasv[nt]);
;         u32x2 ow; ow.x = cvtpk(v[0], v[1]); ow.y = cvtpk(v[2], v[3]);
;         *(GAS u32x2*)(mix + (T0 + pp) * 1024 + c) = ow; } }
	v_mul_f32_e32 v67, v160, v67
	v_mul_f32_e32 v142, v161, v142
	v_cvt_pk_bf16_f32 v166, v67, v142
	v_lshlrev_b32_e32 v67, 16, v51
	v_and_b32_e32 v142, 0xffff0000, v51
	v_mul_f32_e32 v67, v162, v67
	v_mul_f32_e32 v142, v163, v142
	v_cvt_pk_bf16_f32 v167, v67, v142
	v_lshlrev_b32_e32 v67, 16, v56
	v_and_b32_e32 v142, 0xffff0000, v56
	v_mul_f32_e32 v67, v156, v67
	v_mul_f32_e32 v142, v157, v142
	v_cvt_pk_bf16_f32 v156, v67, v142
	v_lshlrev_b32_e32 v67, 16, v57
	v_and_b32_e32 v142, 0xffff0000, v57
	v_mul_f32_e32 v67, v158, v67
	v_mul_f32_e32 v142, v159, v142
	v_cvt_pk_bf16_f32 v157, v67, v142
	v_lshlrev_b32_e32 v67, 16, v58
	v_and_b32_e32 v142, 0xffff0000, v58
	v_mul_f32_e32 v67, v160, v67
	v_mul_f32_e32 v142, v161, v142
	v_cvt_pk_bf16_f32 v158, v67, v142
	v_lshlrev_b32_e32 v67, 16, v59
	v_and_b32_e32 v142, 0xffff0000, v59
	v_mul_f32_e32 v67, v162, v67
	v_mul_f32_e32 v142, v163, v142
	v_cvt_pk_bf16_f32 v159, v67, v142
	ds_read_b128 v[160:163], v113 offset:128
	s_waitcnt lgkmcnt(0)
	v_mfma_f32_16x16x32_bf16 v[126:129], v[160:163], v[164:167], v[126:129]
	v_lshlrev_b32_e32 v67, 16, v52
	v_and_b32_e32 v142, 0xffff0000, v52
	v_mfma_f32_16x16x32_bf16 v[118:121], v[160:163], v[156:159], v[118:121]
	ds_read_b128 v[160:163], v113 offset:4544
	s_waitcnt lgkmcnt(0)
	v_mfma_f32_16x16x32_bf16 v[134:137], v[160:163], v[164:167], v[134:137]
	v_mfma_f32_16x16x32_bf16 v[130:133], v[160:163], v[156:159], v[130:133]
	ds_read_b128 v[160:163], v113 offset:8704
	s_waitcnt lgkmcnt(0)
	v_mfma_f32_16x16x32_bf16 v[152:155], v[160:163], v[164:167], v[152:155]
	v_mfma_f32_16x16x32_bf16 v[138:141], v[160:163], v[156:159], v[138:141]
	ds_read_b128 v[160:163], v113 offset:13120
	s_waitcnt lgkmcnt(0)
	v_mfma_f32_16x16x32_bf16 v[122:125], v[160:163], v[164:167], v[122:125]
	v_mfma_f32_16x16x32_bf16 v[114:117], v[160:163], v[156:159], v[114:117]
	ds_read_b128 v[156:159], v110 offset:35200
	ds_read_b128 v[160:163], v110 offset:35216
	s_waitcnt lgkmcnt(1)
	v_mul_f32_e32 v67, v156, v67
	v_mul_f32_e32 v142, v157, v142
	v_cvt_pk_bf16_f32 v164, v67, v142
	v_lshlrev_b32_e32 v67, 16, v53
	v_and_b32_e32 v142, 0xffff0000, v53
	v_mul_f32_e32 v67, v158, v67
	v_mul_f32_e32 v142, v159, v142
	v_cvt_pk_bf16_f32 v165, v67, v142
	v_lshlrev_b32_e32 v67, 16, v54
	v_and_b32_e32 v142, 0xffff0000, v54
	s_waitcnt lgkmcnt(0)
	v_mul_f32_e32 v67, v160, v67
	v_mul_f32_e32 v142, v161, v142
	v_cvt_pk_bf16_f32 v166, v67, v142
	v_lshlrev_b32_e32 v67, 16, v55
	v_and_b32_e32 v142, 0xffff0000, v55
	v_mul_f32_e32 v67, v162, v67
	v_mul_f32_e32 v142, v163, v142
	v_cvt_pk_bf16_f32 v167, v67, v142
	v_lshlrev_b32_e32 v67, 16, v60
	v_and_b32_e32 v142, 0xffff0000, v60
	v_mul_f32_e32 v67, v156, v67
	v_mul_f32_e32 v142, v157, v142
	v_cvt_pk_bf16_f32 v156, v67, v142
	v_lshlrev_b32_e32 v67, 16, v61
	v_and_b32_e32 v142, 0xffff0000, v61
	v_mul_f32_e32 v67, v158, v67
	v_mul_f32_e32 v142, v159, v142
	v_cvt_pk_bf16_f32 v157, v67, v142
	v_lshlrev_b32_e32 v67, 16, v62
	v_and_b32_e32 v142, 0xffff0000, v62
	v_mul_f32_e32 v67, v160, v67
	v_mul_f32_e32 v142, v161, v142
	v_cvt_pk_bf16_f32 v158, v67, v142
	v_lshlrev_b32_e32 v67, 16, v63
	v_and_b32_e32 v142, 0xffff0000, v63
	v_mul_f32_e32 v67, v162, v67
	v_mul_f32_e32 v142, v163, v142
	v_cvt_pk_bf16_f32 v159, v67, v142
	ds_read_b128 v[160:163], v113 offset:192
	s_waitcnt lgkmcnt(0)
	v_mfma_f32_16x16x32_bf16 v[126:129], v[160:163], v[164:167], v[126:129]
	v_lshl_add_u64 v[142:143], s[42:43], 0, v[84:85]
	v_or_b32_e32 v67, s2, v111
	v_lshlrev_b64 v[142:143], 11, v[142:143]
	v_mfma_f32_16x16x32_bf16 v[118:121], v[160:163], v[156:159], v[118:121]
	ds_read_b128 v[160:163], v113 offset:4480
	s_nop 2
	v_pk_fma_f32 v[128:129], v[46:47], v[128:129], v[90:91] op_sel_hi:[1,1,0]
	v_pk_fma_f32 v[126:127], v[44:45], v[126:127], v[90:91] op_sel_hi:[1,1,0]
	s_waitcnt lgkmcnt(0)
	v_mfma_f32_16x16x32_bf16 v[134:137], v[160:163], v[164:167], v[134:137]
	v_mul_f32_e64 v108, v128, v108
	v_mul_f32_e64 v109, v129, v109
	v_pk_mul_f32 v[126:127], v[126:127], v[146:147]
	v_lshl_add_u64 v[142:143], s[20:21], 0, v[142:143]
	v_mfma_f32_16x16x32_bf16 v[130:133], v[160:163], v[156:159], v[130:133]
	ds_read_b128 v[160:163], v113 offset:8768
	s_nop 1
	v_pk_fma_f32 v[136:137], v[42:43], v[136:137], v[90:91] op_sel_hi:[1,1,0]
	v_pk_fma_f32 v[134:135], v[40:41], v[134:135], v[90:91] op_sel_hi:[1,1,0]
	s_waitcnt lgkmcnt(0)
; #define GAS __attribute__((address_space(1)))
; __device__ __forceinline__ unsigned cvtpk(float lo, float hi) { unsigned r; asm volatile("v_cvt_pk_bf16_f32 %0, %1, %2" : "=v"(r) : "v"(lo), "v"(hi)); return r; }
; __device__ __forceinline__ float bflo(unsigned w) { return __uint_as_float(w << 16); }
; __device__ __forceinline__ float bfhi(unsigned w) { return __uint_as_float(w & 0xffff0000u); }
; __device__ __forceinline__ void sgu_phase(const Params& p, int o, char* lds) {
;     ...
; #pragma unroll
;     for (int nt = 0; nt < 2; ++nt) { const int pp = wr * 32 + nt * 16 + fr;
; #pragma unroll
;       for (int mt = 0; mt < 4; ++mt) { const int c = g * 128 + wc * 64 + mt * 16 + 4 * quad; const u32x2 uu = uw[nt][mt];
;         const f32x4 v = (f32x4){bflo(uu.x), bfhi(uu.x), bflo(uu.y), bfhi(uu.y)} * (gainv[mt] * acc[mt][nt] + biasv[nt]);
;         u32x2 ow; ow.x = cvtpk(v[0], v[1]); ow.y = cvtpk(v[2], v[3]);
;         *(GAS u32x2*)(mix + (T0 + pp) * 1024 + c) = ow; } }
	v_mfma_f32_16x16x32_bf16 v[152:155], v[160:163], v[164:167], v[152:155]
	v_fma_f32 v118, v44, v118, v92
	v_fma_f32 v119, v45, v119, v92
	v_readlane_b32 s2, v254, 25
	s_add_i32 s35, s35, s2
	v_mfma_f32_16x16x32_bf16 v[138:141], v[160:163], v[156:159], v[138:141]
	ds_read_b128 v[160:163], v113 offset:13056
	v_cvt_pk_bf16_f32 v126, v126, v127
	v_cvt_pk_bf16_f32 v127, v108, v109
	v_lshlrev_b32_e32 v108, 1, v67
	v_mov_b32_e32 v109, v144
	v_lshl_add_u64 v[128:129], v[142:143], 0, v[108:109]
	global_store_dwordx2 v[128:129], v[126:127], off
	s_waitcnt vmcnt(7)
	v_lshlrev_b32_e32 v126, 16, v106
	v_and_b32_e32 v127, 0xffff0000, v106
	v_lshlrev_b32_e32 v106, 16, v107
	v_and_b32_e32 v107, 0xffff0000, v107
	s_waitcnt lgkmcnt(0)
	v_mfma_f32_16x16x32_bf16 v[122:125], v[160:163], v[164:167], v[122:125]
	v_mul_f32_e64 v106, v136, v106
	v_mul_f32_e64 v107, v137, v107
	v_pk_mul_f32 v[126:127], v[134:135], v[126:127]
	v_pk_fma_f32 v[134:135], v[36:37], v[152:153], v[90:91] op_sel_hi:[1,1,0]
	v_cvt_pk_bf16_f32 v126, v126, v127
	v_cvt_pk_bf16_f32 v127, v106, v107
	s_waitcnt vmcnt(6)
	v_lshlrev_b32_e32 v106, 16, v104
	v_and_b32_e32 v107, 0xffff0000, v104
	global_store_dwordx2 v[128:129], v[126:127], off offset:32
	v_lshlrev_b32_e32 v104, 16, v105
	v_and_b32_e32 v105, 0xffff0000, v105
	v_pk_fma_f32 v[126:127], v[38:39], v[154:155], v[90:91] op_sel_hi:[1,1,0]
	v_pk_mul_f32 v[106:107], v[134:135], v[106:107]
	v_pk_mul_f32 v[104:105], v[126:127], v[104:105]
	v_cvt_pk_bf16_f32 v106, v106, v107
	v_pk_fma_f32 v[122:123], v[32:33], v[122:123], v[90:91] op_sel_hi:[1,1,0]
	v_cvt_pk_bf16_f32 v107, v104, v105
	global_store_dwordx2 v[128:129], v[106:107], off offset:64
	s_waitcnt vmcnt(7)
	v_lshlrev_b32_e32 v104, 16, v102
	v_and_b32_e32 v105, 0xffff0000, v102
	v_lshlrev_b32_e32 v102, 16, v103
	v_and_b32_e32 v103, 0xffff0000, v103
	v_pk_fma_f32 v[106:107], v[34:35], v[124:125], v[90:91] op_sel_hi:[1,1,0]
	v_pk_mul_f32 v[104:105], v[122:123], v[104:105]
	v_pk_mul_f32 v[102:103], v[106:107], v[102:103]
	v_cvt_pk_bf16_f32 v104, v104, v105
	v_pk_fma_f32 v[106:107], v[46:47], v[120:121], v[92:93] op_sel_hi:[1,1,0]
	v_cvt_pk_bf16_f32 v105, v102, v103
	v_lshl_add_u64 v[102:103], s[42:43], 0, v[86:87]
	global_store_dwordx2 v[128:129], v[104:105], off offset:96
	v_lshlrev_b64 v[102:103], 11, v[102:103]
	s_waitcnt vmcnt(7)
	v_lshlrev_b32_e32 v104, 16, v100
	v_and_b32_e32 v105, 0xffff0000, v100
	v_lshlrev_b32_e32 v100, 16, v101
	v_and_b32_e32 v101, 0xffff0000, v101
	v_lshl_add_u64 v[102:103], s[20:21], 0, v[102:103]
	v_pk_mul_f32 v[100:101], v[106:107], v[100:101]
	v_pk_mul_f32 v[104:105], v[118:119], v[104:105]
	v_pk_fma_f32 v[106:107], v[40:41], v[130:131], v[92:93] op_sel_hi:[1,1,0]
	v_cvt_pk_bf16_f32 v104, v104, v105
	v_cvt_pk_bf16_f32 v105, v100, v101
	v_lshl_add_u64 v[100:101], v[102:103], 0, v[108:109]
	s_waitcnt vmcnt(6)
	v_lshlrev_b32_e32 v102, 16, v98
	v_and_b32_e32 v103, 0xffff0000, v98
	v_mfma_f32_16x16x32_bf16 v[114:117], v[160:163], v[156:159], v[114:117]
	global_store_dwordx2 v[100:101], v[104:105], off
	v_lshlrev_b32_e32 v98, 16, v99
	v_and_b32_e32 v99, 0xffff0000, v99
	v_pk_fma_f32 v[104:105], v[42:43], v[132:133], v[92:93] op_sel_hi:[1,1,0]
	v_pk_mul_f32 v[102:103], v[106:107], v[102:103]
	v_pk_mul_f32 v[98:99], v[104:105], v[98:99]
	v_cvt_pk_bf16_f32 v102, v102, v103
	v_pk_fma_f32 v[104:105], v[36:37], v[138:139], v[92:93] op_sel_hi:[1,1,0]
	v_cvt_pk_bf16_f32 v103, v98, v99
	global_store_dwordx2 v[100:101], v[102:103], off offset:32
	s_waitcnt vmcnt(7)
	v_lshlrev_b32_e32 v98, 16, v96
	v_and_b32_e32 v99, 0xffff0000, v96
	v_lshlrev_b32_e32 v96, 16, v97
	v_and_b32_e32 v97, 0xffff0000, v97
	v_pk_fma_f32 v[102:103], v[38:39], v[140:141], v[92:93] op_sel_hi:[1,1,0]
	v_pk_mul_f32 v[98:99], v[104:105], v[98:99]
	v_pk_mul_f32 v[96:97], v[102:103], v[96:97]
	v_cvt_pk_bf16_f32 v98, v98, v99
	v_pk_fma_f32 v[102:103], v[32:33], v[114:115], v[92:93] op_sel_hi:[1,1,0]
	v_cvt_pk_bf16_f32 v99, v96, v97
	s_waitcnt vmcnt(6)
	v_lshlrev_b32_e32 v96, 16, v94
	v_and_b32_e32 v97, 0xffff0000, v94
	global_store_dwordx2 v[100:101], v[98:99], off offset:64
	v_lshlrev_b32_e32 v94, 16, v95
	v_and_b32_e32 v95, 0xffff0000, v95
	v_pk_fma_f32 v[98:99], v[34:35], v[116:117], v[92:93] op_sel_hi:[1,1,0]
	v_pk_mul_f32 v[96:97], v[102:103], v[96:97]
	v_pk_mul_f32 v[94:95], v[98:99], v[94:95]
	v_cvt_pk_bf16_f32 v96, v96, v97
	s_nop 0
	v_cvt_pk_bf16_f32 v97, v94, v95
	global_store_dwordx2 v[100:101], v[96:97], off offset:96
	s_cbranch_vccz .LBB0_39

; __device__ __forceinline__ float ss2f(unsigned long long v) { return (float)v * (1.0f / 16777216.0f); }
; __device__ __forceinline__ void sgu_phase(const Params& p, int o, char* lds) {
;     ...
; #pragma unroll
;     for (int i = 0; i < 4; ++i) { const int q = sq0 + 32 * i; const u32x4 w = vst[i];
;       unsigned short* d = (unsigned short*)(lds + OFF_VT + (sc8) * VT_PITCH + q * 2);
;       d[0 * (VT_PITCH / 2)] = (unsigned short)(w.x & 0xffffu); d[1 * (VT_PITCH / 2)] = (unsigned short)(w.x >> 16);
;       d[2 * (VT_PITCH / 2)] = (unsigned short)(w.y & 0xffffu); d[3 * (VT_PITCH / 2)] = (unsigned short)(w.y >> 16);
;       d[4 * (VT_PITCH / 2)] = (unsigned short)(w.z & 0xffffu); d[5 * (VT_PITCH / 2)] = (unsigned short)(w.z >> 16);
;       d[6 * (VT_PITCH / 2)] = (unsigned short)(w.w & 0xffffu); d[7 * (VT_PITCH / 2)] = (unsigned short)(w.w >> 16); }
;     if (tid < 128) rs[tid] = __builtin_amdgcn_rsqf(pg8::ss2f(vsn) * (1.0f / 1024.0f) + EPS);
.LBB0_34:
	s_ashr_i32 s0, s8, 3
	s_ashr_i32 s1, s0, 31
	s_lshl_b64 s[42:43], s[0:1], 7
	v_lshl_add_u64 v[94:95], s[42:43], 0, v[70:71]
	s_lshl_b32 s0, s2, 1
	s_mov_b32 s1, s3
	v_lshl_add_u64 v[96:97], v[74:75], 0, s[0:1]
	v_lshlrev_b64 v[94:95], 12, v[94:95]
	v_lshl_add_u64 v[94:95], v[96:97], 0, v[94:95]
	global_load_dwordx2 v[108:109], v[94:95], off
	global_load_dwordx2 v[106:107], v[94:95], off offset:32
	global_load_dwordx2 v[104:105], v[94:95], off offset:64
	global_load_dwordx2 v[102:103], v[94:95], off offset:96
	v_add_co_u32_e32 v94, vcc, s11, v94
	s_nop 1
	v_addc_co_u32_e32 v95, vcc, 0, v95, vcc
	global_load_dwordx2 v[100:101], v[94:95], off
	global_load_dwordx2 v[98:99], v[94:95], off offset:32
	global_load_dwordx2 v[96:97], v[94:95], off offset:64
	s_nop 0
	global_load_dwordx2 v[94:95], v[94:95], off offset:96
	s_barrier
	s_waitcnt vmcnt(11)
	ds_write_b16 v172, v0
	ds_write_b16_d16_hi v172, v0 offset:272
	ds_write_b16 v172, v1 offset:544
	ds_write_b16_d16_hi v172, v1 offset:816
	ds_write_b16 v172, v2 offset:1088
	ds_write_b16_d16_hi v172, v2 offset:1360
	ds_write_b16 v172, v3 offset:1632
	ds_write_b16_d16_hi v172, v3 offset:1904
	s_waitcnt vmcnt(10)
	ds_write_b16 v173, v4
	ds_write_b16_d16_hi v173, v4 offset:272
	ds_write_b16 v173, v5 offset:544
	ds_write_b16_d16_hi v173, v5 offset:816
	ds_write_b16 v173, v6 offset:1088
	ds_write_b16_d16_hi v173, v6 offset:1360
	ds_write_b16 v173, v7 offset:1632
	ds_write_b16_d16_hi v173, v7 offset:1904
	s_waitcnt vmcnt(9)
	ds_write_b16 v174, v8
	ds_write_b16_d16_hi v174, v8 offset:272
	ds_write_b16 v174, v9 offset:544
	ds_write_b16_d16_hi v174, v9 offset:816
	ds_write_b16 v174, v10 offset:1088
	ds_write_b16_d16_hi v174, v10 offset:1360
	ds_write_b16 v174, v11 offset:1632
	ds_write_b16_d16_hi v174, v11 offset:1904
	s_waitcnt vmcnt(8)
	ds_write_b16 v175, v12
	ds_write_b16_d16_hi v175, v12 offset:272
	ds_write_b16 v175, v13 offset:544
	ds_write_b16_d16_hi v175, v13 offset:816
	ds_write_b16 v175, v14 offset:1088
	ds_write_b16_d16_hi v175, v14 offset:1360
	ds_write_b16 v175, v15 offset:1632
	ds_write_b16_d16_hi v175, v15 offset:1904
	s_and_saveexec_b64 s[0:1], s[40:41]
	s_cbranch_execz .LBB0_36
	v_ffbh_u32_e32 v67, v69
	v_min_u32_e32 v67, 32, v67
	v_lshlrev_b64 v[114:115], v67, v[68:69]
	v_min_u32_e32 v114, 1, v114
	v_or_b32_e32 v114, v115, v114
	v_cvt_f32_u32_e32 v114, v114
	v_sub_u32_e32 v67, 32, v67
	v_ldexp_f32 v67, v114, v67
	v_mul_f32_e32 v67, 0x33800000, v67
	v_fmamk_f32 v67, v67, 0x3a800000, v233
	v_rsq_f32_e32 v67, v67
	ds_write_b32 v93, v67 offset:34816
